# v82 + phase-4 lag ~13 us for workgroups without a GLU tile
# speedup vs baseline: 1.0194x; 1.0026x over previous
.LBB0_589:
	s_cmp_gt_i32 s26, 4
	s_cselect_b64 s[4:5], -1, 0
	s_xor_b64 s[0:1], s[0:1], -1
	s_or_b64 s[0:1], s[4:5], s[0:1]
	s_and_b64 vcc, exec, s[0:1]
	s_cbranch_vccnz .LBB0_771
	s_cmpk_lt_u32 s96, 0x80
	s_cbranch_scc1 .Lp4_lag
	s_sleep 127
	s_sleep 127
	s_sleep 127
	s_sleep 100
